# stack + attention fast-path loop head aligned to 64 bytes
# speedup vs baseline: 1.0009x; 1.0009x over previous
.LBB0_456:
	s_mov_b32 s99, s98
	.p2align 6
